# group-B stick-breaking prompt tile: all 16 K-fragment loads issued together at tile top; on top of v28
# baseline (speedup 1.0000x reference)
.LBB0_381:
	s_cmp_eq_u32 s81, 0
	s_cselect_b64 s[78:79], -1, 0
	s_lshl_b64 s[6:7], s[54:55], 12
	v_lshl_add_u64 v[66:67], v[200:201], 0, s[6:7]
	v_lshl_add_u64 v[94:95], v[196:197], 1, v[66:67]
	s_mov_b64 s[8:9], 0x20000
	v_lshl_add_u64 v[96:97], v[94:95], 0, s[8:9]
	global_load_dwordx4 v[66:69], v[94:95], off
	global_load_dwordx4 v[82:85], v[94:95], off offset:32
	global_load_dwordx4 v[86:89], v[94:95], off offset:64
	global_load_dwordx4 v[130:133], v[94:95], off offset:96
	global_load_dwordx4 v[134:137], v[94:95], off offset:128
	global_load_dwordx4 v[138:141], v[94:95], off offset:160
	global_load_dwordx4 v[90:93], v[94:95], off offset:192
	global_load_dwordx4 v[234:237], v[94:95], off offset:224
	global_load_dwordx4 v[142:145], v[96:97], off
	global_load_dwordx4 v[146:149], v[96:97], off offset:32
	global_load_dwordx4 v[154:157], v[96:97], off offset:64
	global_load_dwordx4 v[162:165], v[96:97], off offset:96
	global_load_dwordx4 v[170:173], v[96:97], off offset:128
	global_load_dwordx4 v[178:181], v[96:97], off offset:160
	global_load_dwordx4 v[186:189], v[96:97], off offset:192
	global_load_dwordx4 v[190:193], v[96:97], off offset:224
	s_waitcnt vmcnt(15)
	v_mfma_f32_32x32x16_bf16 v[66:81], v[66:69], v[98:101], 0
	s_waitcnt vmcnt(14)
	v_mfma_f32_32x32x16_bf16 v[66:81], v[82:85], v[102:105], v[66:81]
	s_waitcnt vmcnt(13)
	v_mfma_f32_32x32x16_bf16 v[66:81], v[86:89], v[106:109], v[66:81]
	s_waitcnt vmcnt(12)
	v_mfma_f32_32x32x16_bf16 v[66:81], v[130:133], v[110:113], v[66:81]
	s_waitcnt vmcnt(11)
	v_mfma_f32_32x32x16_bf16 v[66:81], v[134:137], v[114:117], v[66:81]
	s_waitcnt vmcnt(10)
	v_mfma_f32_32x32x16_bf16 v[66:81], v[138:141], v[118:121], v[66:81]
	s_waitcnt vmcnt(9)
	v_mfma_f32_32x32x16_bf16 v[66:81], v[90:93], v[122:125], v[66:81]
	v_lshl_add_u64 v[238:239], v[198:199], 0, s[6:7]
	v_add_co_u32_e32 v86, vcc, s44, v238
	s_mov_b32 s6, 0x10000
	s_nop 0
	v_addc_co_u32_e32 v87, vcc, 0, v239, vcc
	global_load_dwordx4 v[130:133], v[238:239], off
	global_load_dwordx4 v[134:137], v[86:87], off
	s_waitcnt vmcnt(3)
	v_mfma_f32_32x32x16_bf16 v[82:97], v[142:145], v[98:101], 0
	v_add_co_u32_e32 v138, vcc, s45, v238
	s_nop 1
	v_addc_co_u32_e32 v139, vcc, 0, v239, vcc
	v_add_co_u32_e32 v142, vcc, s46, v238
	v_mfma_f32_32x32x16_bf16 v[82:97], v[146:149], v[102:105], v[82:97]
	s_nop 0
	v_addc_co_u32_e32 v143, vcc, 0, v239, vcc
	v_add_co_u32_e32 v146, vcc, s6, v238
	s_mov_b32 s6, 0x14000
	s_nop 0
	v_addc_co_u32_e32 v147, vcc, 0, v239, vcc
	v_mfma_f32_32x32x16_bf16 v[82:97], v[154:157], v[106:109], v[82:97]
	v_add_co_u32_e32 v150, vcc, s6, v238
	s_mov_b32 s6, 0x18000
	s_nop 0
	v_addc_co_u32_e32 v151, vcc, 0, v239, vcc
	v_add_co_u32_e32 v154, vcc, s6, v238
	v_mfma_f32_32x32x16_bf16 v[82:97], v[162:165], v[110:113], v[82:97]
	s_nop 0
	v_addc_co_u32_e32 v155, vcc, 0, v239, vcc
	s_mov_b32 s6, 0x1c000
	v_add_co_u32_e32 v158, vcc, s6, v238
	s_mov_b32 s6, 0x24000
	s_nop 0
	v_addc_co_u32_e32 v159, vcc, 0, v239, vcc
	v_mfma_f32_32x32x16_bf16 v[82:97], v[170:173], v[114:117], v[82:97]
	v_add_co_u32_e32 v162, vcc, s43, v238
	global_load_dwordx4 v[138:141], v[138:139], off
	s_nop 0
	global_load_dwordx4 v[142:145], v[142:143], off
	v_addc_co_u32_e32 v163, vcc, 0, v239, vcc
	v_add_co_u32_e32 v166, vcc, s6, v238
	v_mfma_f32_32x32x16_bf16 v[82:97], v[178:181], v[118:121], v[82:97]
	s_nop 0
	v_addc_co_u32_e32 v167, vcc, 0, v239, vcc
	s_mov_b32 s6, 0x28000
	v_add_co_u32_e32 v170, vcc, s6, v238
	s_mov_b32 s6, 0x2c000
	s_nop 0
	v_addc_co_u32_e32 v171, vcc, 0, v239, vcc
	v_add_co_u32_e32 v174, vcc, s6, v238
	s_mov_b32 s6, 0x30000
	s_nop 0
	v_addc_co_u32_e32 v175, vcc, 0, v239, vcc
	v_mfma_f32_32x32x16_bf16 v[82:97], v[186:189], v[122:125], v[82:97]
	v_add_co_u32_e32 v178, vcc, s6, v238
	s_mov_b32 s6, 0x34000
	s_nop 0
	v_addc_co_u32_e32 v179, vcc, 0, v239, vcc
	v_add_co_u32_e32 v182, vcc, s6, v238
	s_mov_b32 s6, 0x38000
	s_nop 0
	v_addc_co_u32_e32 v183, vcc, 0, v239, vcc
	v_add_co_u32_e32 v186, vcc, s6, v238
	s_mov_b32 s6, 0x3c000
	s_nop 0
	v_addc_co_u32_e32 v187, vcc, 0, v239, vcc
	v_add_co_u32_e32 v238, vcc, s6, v238
	global_load_dwordx4 v[146:149], v[146:147], off
	s_nop 0
	global_load_dwordx4 v[150:153], v[150:151], off
	s_nop 0
	global_load_dwordx4 v[154:157], v[154:155], off
	s_nop 0
	global_load_dwordx4 v[158:161], v[158:159], off
	s_nop 0
	global_load_dwordx4 v[162:165], v[162:163], off
	s_nop 0
	global_load_dwordx4 v[166:169], v[166:167], off
	s_nop 0
	global_load_dwordx4 v[170:173], v[170:171], off
	s_nop 0
	global_load_dwordx4 v[174:177], v[174:175], off
	s_nop 0
	global_load_dwordx4 v[178:181], v[178:179], off
	s_nop 0
	global_load_dwordx4 v[182:185], v[182:183], off
	v_addc_co_u32_e32 v239, vcc, 0, v239, vcc
	s_waitcnt vmcnt(14)
	v_mfma_f32_32x32x16_bf16 v[82:97], v[190:193], v[126:129], v[82:97]
	global_load_dwordx4 v[186:189], v[186:187], off
	s_nop 0
	global_load_dwordx4 v[190:193], v[238:239], off
	v_mfma_f32_32x32x16_bf16 v[66:81], v[234:237], v[126:129], v[66:81]
	s_nop 7
	v_mul_f32_e32 v233, 0x3db504f3, v82
	v_mul_f32_e64 v203, |v233|, s48
	v_exp_f32_e32 v234, v203
	v_mul_f32_e32 v236, 0x3db504f3, v83
	v_mul_f32_e64 v237, |v236|, s48
	v_exp_f32_e32 v237, v237
	v_add_f32_e32 v234, 1.0, v234
	v_log_f32_e32 v234, v234
	v_max_f32_e32 v233, 0, v233
	v_min_i32_e32 v203, 64, v214
	v_add_u32_e32 v235, 32, v207
	v_fmac_f32_e32 v233, 0x3f317218, v234
	v_add_f32_e32 v234, 1.0, v237
	v_cmp_ge_i32_e32 vcc, v235, v203
	v_log_f32_e32 v235, v234
	v_max_f32_e32 v234, 0, v236
	v_add_u32_e32 v237, 33, v207
	v_cmp_ge_i32_e64 s[6:7], v237, v203
	v_fmac_f32_e32 v234, 0x3f317218, v235
	v_mul_f32_e32 v235, 0x3db504f3, v84
	v_mul_f32_e64 v236, |v235|, s48
	v_exp_f32_e32 v236, v236
	v_max_f32_e32 v235, 0, v235
	v_add_u32_e32 v238, 34, v207
	v_cmp_ge_i32_e64 s[8:9], v238, v203
	v_add_f32_e32 v236, 1.0, v236
	v_log_f32_e32 v236, v236
	v_fma_f32 v82, v82, s47, -v233
	s_and_b64 vcc, s[78:79], vcc
	v_fma_f32 v83, v83, s47, -v234
	v_fmac_f32_e32 v235, 0x3f317218, v236
	v_mul_f32_e32 v236, 0x3db504f3, v85
	v_mul_f32_e64 v237, |v236|, s48
	v_exp_f32_e32 v237, v237
	v_max_f32_e32 v236, 0, v236
	s_and_b64 s[6:7], s[78:79], s[6:7]
	v_fma_f32 v84, v84, s47, -v235
	v_add_f32_e32 v237, 1.0, v237
	v_log_f32_e32 v237, v237
	s_and_b64 s[8:9], s[78:79], s[8:9]
	v_cndmask_b32_e32 v82, v82, v227, vcc
	v_cndmask_b32_e64 v83, v83, v227, s[6:7]
	v_fmac_f32_e32 v236, 0x3f317218, v237
	v_add_u32_e32 v237, 35, v207
	v_cmp_ge_i32_e64 s[10:11], v237, v203
	v_fma_f32 v85, v85, s47, -v236
	s_and_b64 s[10:11], s[78:79], s[10:11]
	v_cndmask_b32_e64 v84, v84, v227, s[8:9]
	v_cndmask_b32_e64 v85, v85, v227, s[10:11]
	v_mul_f32_e32 v237, 0x3db504f3, v86
	v_mul_f32_e64 v238, |v237|, s48
	v_exp_f32_e32 v238, v238
	v_mul_f32_e32 v240, 0x3db504f3, v87
	v_mul_f32_e64 v241, |v240|, s48
	v_exp_f32_e32 v241, v241
	v_add_f32_e32 v238, 1.0, v238
	v_log_f32_e32 v238, v238
	v_max_f32_e32 v237, 0, v237
	v_add_u32_e32 v239, 40, v207
	v_cmp_ge_i32_e64 s[12:13], v239, v203
	v_fmac_f32_e32 v237, 0x3f317218, v238
	v_add_f32_e32 v238, 1.0, v241
	v_log_f32_e32 v238, v238
	v_max_f32_e32 v239, 0, v240
	v_add_u32_e32 v241, 41, v207
	v_cmp_ge_i32_e64 s[14:15], v241, v203
	v_fmac_f32_e32 v239, 0x3f317218, v238
	v_mul_f32_e32 v238, 0x3db504f3, v88
	v_mul_f32_e64 v240, |v238|, s48
	v_exp_f32_e32 v240, v240
	v_max_f32_e32 v238, 0, v238
	v_add_u32_e32 v242, 42, v207
	v_cmp_ge_i32_e64 s[16:17], v242, v203
	v_add_f32_e32 v240, 1.0, v240
	v_log_f32_e32 v240, v240
	s_and_b64 s[16:17], s[78:79], s[16:17]
	v_fma_f32 v86, v86, s47, -v237
	s_and_b64 s[12:13], s[78:79], s[12:13]
	v_fmac_f32_e32 v238, 0x3f317218, v240
	v_mul_f32_e32 v240, 0x3db504f3, v89
	v_mul_f32_e64 v241, |v240|, s48
	v_exp_f32_e32 v241, v241
	v_fma_f32 v88, v88, s47, -v238
	v_cndmask_b32_e64 v242, v88, v227, s[16:17]
	v_max_f32_e32 v88, 0, v240
	v_add_f32_e32 v241, 1.0, v241
	v_log_f32_e32 v241, v241
	v_add_u32_e32 v240, 43, v207
	v_cmp_ge_i32_e64 s[18:19], v240, v203
	v_fma_f32 v87, v87, s47, -v239
	v_fmac_f32_e32 v88, 0x3f317218, v241
	s_and_b64 s[14:15], s[78:79], s[14:15]
	v_fma_f32 v89, v89, s47, -v88
	s_and_b64 s[18:19], s[78:79], s[18:19]
	v_cndmask_b32_e64 v86, v86, v227, s[12:13]
	v_cndmask_b32_e64 v87, v87, v227, s[14:15]
	v_cndmask_b32_e64 v240, v89, v227, s[18:19]
	v_mul_f32_e32 v89, 0x3db504f3, v90
	v_mul_f32_e64 v241, |v89|, s48
	v_exp_f32_e32 v241, v241
	v_mul_f32_e32 v244, 0x3db504f3, v91
	v_mul_f32_e64 v245, |v244|, s48
	v_exp_f32_e32 v245, v245
	v_add_f32_e32 v241, 1.0, v241
	v_log_f32_e32 v241, v241
	v_max_f32_e32 v89, 0, v89
	v_add_u32_e32 v243, 48, v207
	v_cmp_ge_i32_e64 s[20:21], v243, v203
	v_fmac_f32_e32 v89, 0x3f317218, v241
	v_add_f32_e32 v241, 1.0, v245
	v_log_f32_e32 v241, v241
	v_fma_f32 v90, v90, s47, -v89
	s_and_b64 s[20:21], s[78:79], s[20:21]
	v_cndmask_b32_e64 v243, v90, v227, s[20:21]
	v_max_f32_e32 v90, 0, v244
	v_fmac_f32_e32 v90, 0x3f317218, v241
	v_mul_f32_e32 v241, 0x3db504f3, v92
	v_mul_f32_e64 v244, |v241|, s48
	v_exp_f32_e32 v244, v244
	v_add_u32_e32 v245, 49, v207
	v_cmp_ge_i32_e64 s[22:23], v245, v203
	v_fma_f32 v91, v91, s47, -v90
	v_add_f32_e32 v244, 1.0, v244
	v_log_f32_e32 v244, v244
	s_and_b64 s[22:23], s[78:79], s[22:23]
	v_cndmask_b32_e64 v245, v91, v227, s[22:23]
	v_max_f32_e32 v91, 0, v241
	v_mul_f32_e32 v241, 0x3db504f3, v93
	v_fmac_f32_e32 v91, 0x3f317218, v244
	v_mul_f32_e64 v244, |v241|, s48
	v_exp_f32_e32 v244, v244
	v_add_u32_e32 v246, 50, v207
	v_cmp_ge_i32_e64 s[24:25], v246, v203
	v_fma_f32 v92, v92, s47, -v91
	v_add_f32_e32 v244, 1.0, v244
	v_log_f32_e32 v244, v244
	s_and_b64 s[24:25], s[78:79], s[24:25]
	v_cndmask_b32_e64 v246, v92, v227, s[24:25]
	v_max_f32_e32 v92, 0, v241
	v_add_u32_e32 v241, 51, v207
	v_fmac_f32_e32 v92, 0x3f317218, v244
	v_cmp_ge_i32_e64 s[26:27], v241, v203
	v_fma_f32 v93, v93, s47, -v92
	s_and_b64 s[26:27], s[78:79], s[26:27]
	v_cndmask_b32_e64 v241, v93, v227, s[26:27]
	v_mul_f32_e32 v93, 0x3db504f3, v94
	v_mul_f32_e64 v244, |v93|, s48
	v_exp_f32_e32 v244, v244
	v_max_f32_e32 v93, 0, v93
	v_cmp_ge_i32_e64 s[30:31], v208, v203
	s_and_b64 s[30:31], s[78:79], s[30:31]
	v_add_f32_e32 v244, 1.0, v244
	v_log_f32_e32 v244, v244
	v_cmp_ge_i32_e64 s[36:37], v209, v203
	s_and_b64 s[36:37], s[78:79], s[36:37]
	v_cmp_ge_i32_e64 s[38:39], v210, v203
	v_fmac_f32_e32 v93, 0x3f317218, v244
	v_add_u32_e32 v244, 56, v207
	v_cmp_ge_i32_e64 s[28:29], v244, v203
	s_and_b64 s[28:29], s[78:79], s[28:29]
	v_fma_f32 v94, v94, s47, -v93
	v_cndmask_b32_e64 v244, v94, v227, s[28:29]
	v_mul_f32_e32 v94, 0x3db504f3, v95
	v_mul_f32_e64 v247, |v94|, s48
	v_exp_f32_e32 v247, v247
	v_max_f32_e32 v94, 0, v94
	s_and_b64 s[38:39], s[78:79], s[38:39]
	v_add_f32_e32 v247, 1.0, v247
	v_log_f32_e32 v247, v247
	s_nop 0
	v_fmac_f32_e32 v94, 0x3f317218, v247
	v_fma_f32 v95, v95, s47, -v94
	v_cndmask_b32_e64 v247, v95, v227, s[30:31]
	v_mul_f32_e32 v95, 0x3db504f3, v96
	v_mul_f32_e64 v248, |v95|, s48
	v_exp_f32_e32 v248, v248
	v_max_f32_e32 v95, 0, v95
	v_add_f32_e32 v248, 1.0, v248
	v_log_f32_e32 v248, v248
	s_nop 0
	v_fmac_f32_e32 v95, 0x3f317218, v248
	v_fma_f32 v96, v96, s47, -v95
	v_cndmask_b32_e64 v248, v96, v227, s[36:37]
	v_mul_f32_e32 v96, 0x3db504f3, v97
	v_mul_f32_e64 v249, |v96|, s48
	v_exp_f32_e32 v249, v249
	v_max_f32_e32 v96, 0, v96
	v_add_f32_e32 v249, 1.0, v249
	v_log_f32_e32 v249, v249
	s_nop 0
	v_fmac_f32_e32 v96, 0x3f317218, v249
	v_fma_f32 v97, v97, s47, -v96
	v_cndmask_b32_e64 v249, v97, v227, s[38:39]
	v_cndmask_b32_e64 v250, -v96, 0, s[38:39]
	v_cndmask_b32_e64 v96, -v95, 0, s[36:37]
	v_cndmask_b32_e64 v97, -v93, 0, s[28:29]
	v_cndmask_b32_e64 v254, -v88, 0, s[18:19]
	v_cndmask_b32_e64 v93, -v238, 0, s[16:17]
	v_cndmask_b32_e64 v238, -v239, 0, s[14:15]
	v_cndmask_b32_e64 v95, -v237, 0, s[12:13]
	v_cndmask_b32_e64 v252, -v92, 0, s[26:27]
	v_cndmask_b32_e64 v92, -v233, 0, vcc
	v_add_f32_e32 v95, v95, v238
	v_add_f32_e32 v233, v93, v254
	v_add_f32_e32 v93, v95, v233
	v_cndmask_b32_e64 v251, -v94, 0, s[30:31]
	v_cndmask_b32_e64 v94, -v234, 0, s[6:7]
	v_mov_b32_e32 v95, v93
	v_mov_b32_e32 v234, v93
	v_cndmask_b32_e64 v91, -v91, 0, s[24:25]
	v_cndmask_b32_e64 v253, -v90, 0, s[22:23]
	v_cndmask_b32_e64 v89, -v89, 0, s[20:21]
	v_permlane32_swap_b32_e32 v95, v234
	v_cndmask_b32_e64 v95, v95, v234, s[4:5]
	v_add_f32_e32 v89, v89, v253
	v_add_f32_e32 v234, v91, v252
	v_add_f32_e32 v89, v89, v234
	v_cndmask_b32_e64 v90, -v235, 0, s[8:9]
	v_mov_b32_e32 v91, v89
	v_mov_b32_e32 v235, v89
	s_nop 1
	v_permlane32_swap_b32_e32 v91, v235
	v_cndmask_b32_e64 v235, v91, v235, s[4:5]
	v_cndmask_b32_e64 v88, -v236, 0, s[10:11]
	v_add_f32_e32 v91, v89, v235
	v_add_f32_e32 v89, v97, v251
	v_add_f32_e32 v236, v96, v250
	v_add_f32_e32 v89, v89, v236
	v_mov_b32_e32 v96, v89
	v_mov_b32_e32 v97, v89
	s_nop 1
	v_permlane32_swap_b32_e32 v96, v97
	v_cndmask_b32_e64 v237, v96, v97, s[4:5]
	v_add_f32_e32 v89, v89, v237
	v_pk_add_f32 v[92:93], v[92:93], v[94:95]
	v_pk_add_f32 v[96:97], v[90:91], v[88:89]
	s_nop 0
	v_pk_add_f32 v[92:93], v[92:93], v[96:97]
	v_add_f32_e32 v94, v94, v96
	v_mov_b32_e32 v90, v92
	v_mov_b32_e32 v91, v92
	s_nop 1
	v_permlane32_swap_b32_e32 v90, v91
	v_cndmask_b32_e64 v90, v90, v91, s[4:5]
	v_add_f32_e32 v91, v202, v93
	v_cndmask_b32_e64 v239, 0, v90, s[4:5]
	v_add_f32_e32 v91, v239, v91
	v_add_f32_e32 v84, v84, v91
	v_add_f32_e32 v83, v83, v91
	v_add_f32_e32 v82, v82, v91
	v_add_f32_e32 v85, v85, v91
	v_add_f32_e32 v84, v88, v84
	v_add_f32_e32 v83, v96, v83
	v_add_f32_e32 v82, v94, v82
	v_mul_f32_e32 v85, 0x3fb8aa3b, v85
	v_mul_f32_e32 v84, 0x3fb8aa3b, v84
	v_mul_f32_e32 v83, 0x3fb8aa3b, v83
	v_mul_f32_e32 v82, 0x3fb8aa3b, v82
	v_exp_f32_e32 v85, v85
	v_exp_f32_e32 v84, v84
	v_exp_f32_e32 v83, v83
	v_exp_f32_e32 v82, v82
	v_add_f32_e32 v88, v202, v97
	v_cndmask_b32_e64 v91, 0, v95, s[4:5]
	v_add_f32_e32 v88, v91, v88
	v_add_f32_e32 v91, v238, v233
	v_add_f32_e32 v95, v242, v88
	v_add_f32_e32 v87, v87, v88
	v_add_f32_e32 v86, v86, v88
	v_add_f32_e32 v94, v240, v88
	v_add_f32_e32 v95, v254, v95
	v_add_f32_e32 v87, v233, v87
	v_add_f32_e32 v86, v91, v86
	v_mul_f32_e32 v94, 0x3fb8aa3b, v94
	v_mul_f32_e32 v95, 0x3fb8aa3b, v95
	v_mul_f32_e32 v87, 0x3fb8aa3b, v87
	v_mul_f32_e32 v86, 0x3fb8aa3b, v86
	v_exp_f32_e32 v94, v94
	v_exp_f32_e32 v95, v95
	v_exp_f32_e32 v96, v87
	v_exp_f32_e32 v88, v86
	v_add_f32_e32 v86, v202, v89
	v_cndmask_b32_e64 v87, 0, v235, s[4:5]
	v_add_f32_e32 v86, v87, v86
	v_add_f32_e32 v89, v241, v86
	v_mul_f32_e32 v89, 0x3fb8aa3b, v89
	v_exp_f32_e32 v91, v89
	v_add_f32_e32 v89, v246, v86
	v_add_f32_e32 v89, v252, v89
	v_mul_f32_e32 v89, 0x3fb8aa3b, v89
	v_add_f32_e32 v87, v253, v234
	v_exp_f32_e32 v97, v89
	v_add_f32_e32 v89, v245, v86
	v_add_f32_e32 v86, v243, v86
	v_add_f32_e32 v89, v234, v89
	v_add_f32_e32 v86, v87, v86
	v_mul_f32_e32 v89, 0x3fb8aa3b, v89
	v_mul_f32_e32 v86, 0x3fb8aa3b, v86
	v_exp_f32_e32 v233, v89
	v_exp_f32_e32 v234, v86
	v_add_f32_e32 v86, 0, v202
	v_cndmask_b32_e64 v87, 0, v237, s[4:5]
	v_add_f32_e32 v86, v86, v87
	v_add_f32_e32 v89, v249, v86
	v_mul_f32_e32 v89, 0x3fb8aa3b, v89
	v_exp_f32_e32 v235, v89
	v_add_f32_e32 v89, v248, v86
	v_add_f32_e32 v89, v250, v89
	v_mul_f32_e32 v89, 0x3fb8aa3b, v89
	v_add_f32_e32 v87, v251, v236
	v_exp_f32_e32 v237, v89
	v_add_f32_e32 v89, v247, v86
	v_add_f32_e32 v86, v244, v86
	v_add_f32_e32 v89, v236, v89
	v_add_f32_e32 v86, v87, v86
	v_mul_f32_e32 v89, 0x3fb8aa3b, v89
	v_mul_f32_e32 v86, 0x3fb8aa3b, v86
	v_exp_f32_e32 v236, v89
	v_exp_f32_e32 v238, v86
	v_cvt_pk_bf16_f32 v86, v82, v83
	v_cvt_pk_bf16_f32 v83, v97, v91
	v_mul_f32_e32 v91, 0x3db504f3, v66
	v_cvt_pk_bf16_f32 v89, v95, v94
	v_mul_f32_e64 v94, |v91|, s48
	v_exp_f32_e32 v95, v94
	v_max_f32_e32 v94, 0, v91
	v_cvt_pk_bf16_f32 v88, v88, v96
	v_cvt_pk_bf16_f32 v82, v234, v233
	v_add_f32_e32 v91, 1.0, v95
	v_mul_f32_e32 v95, 0x3db504f3, v67
	v_mul_f32_e64 v96, |v95|, s48
	v_log_f32_e32 v91, v91
	v_exp_f32_e32 v96, v96
	v_max_f32_e32 v95, 0, v95
	v_cmp_ge_i32_e32 vcc, v207, v203
	v_fmac_f32_e32 v94, 0x3f317218, v91
	v_add_f32_e32 v91, 1.0, v96
	v_log_f32_e32 v91, v91
	v_cmp_ge_i32_e64 s[6:7], v211, v203
	v_cmp_ge_i32_e64 s[8:9], v212, v203
	v_cmp_ge_i32_e64 s[10:11], v213, v203
	v_fmac_f32_e32 v95, 0x3f317218, v91
	v_mul_f32_e32 v91, 0x3db504f3, v68
	v_mul_f32_e64 v96, |v91|, s48
	v_exp_f32_e32 v97, v96
	v_max_f32_e32 v96, 0, v91
	v_cvt_pk_bf16_f32 v87, v84, v85
	v_cvt_pk_bf16_f32 v84, v238, v236
	v_add_f32_e32 v91, 1.0, v97
	v_mul_f32_e32 v97, 0x3db504f3, v69
	v_mul_f32_e64 v233, |v97|, s48
	v_log_f32_e32 v91, v91
	v_exp_f32_e32 v233, v233
	v_max_f32_e32 v97, 0, v97
	v_fma_f32 v66, v66, s47, -v94
	v_fmac_f32_e32 v96, 0x3f317218, v91
	v_add_f32_e32 v91, 1.0, v233
	v_log_f32_e32 v91, v91
	s_and_b64 vcc, s[78:79], vcc
	v_fma_f32 v67, v67, s47, -v95
	s_and_b64 s[6:7], s[78:79], s[6:7]
	v_fmac_f32_e32 v97, 0x3f317218, v91
	v_fma_f32 v68, v68, s47, -v96
	s_and_b64 s[8:9], s[78:79], s[8:9]
	v_fma_f32 v69, v69, s47, -v97
	s_and_b64 s[10:11], s[78:79], s[10:11]
	v_permlane32_swap_b32_e32 v86, v88
	v_cvt_pk_bf16_f32 v85, v237, v235
	v_permlane32_swap_b32_e32 v82, v84
	v_cndmask_b32_e32 v66, v66, v227, vcc
	v_cndmask_b32_e64 v67, v67, v227, s[6:7]
	v_cndmask_b32_e64 v68, v68, v227, s[8:9]
	v_cndmask_b32_e64 v69, v69, v227, s[10:11]
	v_mul_f32_e32 v91, 0x3db504f3, v70
	v_mul_f32_e64 v233, |v91|, s48
	v_mul_f32_e32 v234, 0x3db504f3, v71
	v_exp_f32_e32 v233, v233
	v_mul_f32_e64 v235, |v234|, s48
	v_exp_f32_e32 v235, v235
	v_max_f32_e32 v236, 0, v91
	v_add_f32_e32 v233, 1.0, v233
	v_log_f32_e32 v233, v233
	v_add_f32_e32 v91, 1.0, v235
	v_log_f32_e32 v91, v91
	v_cmp_ge_i32_e64 s[16:17], v218, v203
	v_fmac_f32_e32 v236, 0x3f317218, v233
	v_max_f32_e32 v233, 0, v234
	v_fmac_f32_e32 v233, 0x3f317218, v91
	v_mul_f32_e32 v91, 0x3db504f3, v72
	v_mul_f32_e64 v234, |v91|, s48
	v_exp_f32_e32 v234, v234
	v_max_f32_e32 v235, 0, v91
	s_and_b64 s[16:17], s[78:79], s[16:17]
	v_cmp_ge_i32_e64 s[12:13], v216, v203
	v_add_f32_e32 v91, 1.0, v234
	v_mul_f32_e32 v234, 0x3db504f3, v73
	v_mul_f32_e64 v237, |v234|, s48
	v_log_f32_e32 v91, v91
	v_exp_f32_e32 v237, v237
	v_cmp_ge_i32_e64 s[14:15], v217, v203
	v_cmp_ge_i32_e64 s[18:19], v219, v203
	v_fmac_f32_e32 v235, 0x3f317218, v91
	v_add_f32_e32 v91, 1.0, v237
	v_log_f32_e32 v91, v91
	v_fma_f32 v72, v72, s47, -v235
	v_cndmask_b32_e64 v237, v72, v227, s[16:17]
	v_max_f32_e32 v72, 0, v234
	v_fmac_f32_e32 v72, 0x3f317218, v91
	v_fma_f32 v70, v70, s47, -v236
	s_and_b64 s[12:13], s[78:79], s[12:13]
	v_fma_f32 v71, v71, s47, -v233
	s_and_b64 s[14:15], s[78:79], s[14:15]
	v_fma_f32 v73, v73, s47, -v72
	s_and_b64 s[18:19], s[78:79], s[18:19]
	v_cndmask_b32_e64 v70, v70, v227, s[12:13]
	v_cndmask_b32_e64 v71, v71, v227, s[14:15]
	v_cndmask_b32_e64 v234, v73, v227, s[18:19]
	v_mul_f32_e32 v73, 0x3db504f3, v74
	v_mul_f32_e64 v91, |v73|, s48
	v_exp_f32_e32 v91, v91
	v_mul_f32_e32 v238, 0x3db504f3, v75
	v_mul_f32_e64 v239, |v238|, s48
	v_exp_f32_e32 v239, v239
	v_add_f32_e32 v91, 1.0, v91
	v_log_f32_e32 v91, v91
	v_max_f32_e32 v240, 0, v73
	v_add_f32_e32 v73, 1.0, v239
	v_log_f32_e32 v73, v73
	v_cmp_ge_i32_e64 s[20:21], v220, v203
	v_fmac_f32_e32 v240, 0x3f317218, v91
	v_fma_f32 v74, v74, s47, -v240
	s_and_b64 s[20:21], s[78:79], s[20:21]
	v_cndmask_b32_e64 v239, v74, v227, s[20:21]
	v_max_f32_e32 v74, 0, v238
	v_fmac_f32_e32 v74, 0x3f317218, v73
	v_fma_f32 v73, v75, s47, -v74
	v_mul_f32_e32 v75, 0x3db504f3, v76
	v_mul_f32_e64 v91, |v75|, s48
	v_exp_f32_e32 v91, v91
	v_cmp_ge_i32_e64 s[22:23], v221, v203
	s_and_b64 s[22:23], s[78:79], s[22:23]
	v_max_f32_e32 v75, 0, v75
	v_cndmask_b32_e64 v238, v73, v227, s[22:23]
	v_add_f32_e32 v73, 1.0, v91
	v_mul_f32_e32 v91, 0x3db504f3, v77
	v_log_f32_e32 v73, v73
	v_mul_f32_e64 v241, |v91|, s48
	v_exp_f32_e32 v241, v241
	v_cmp_ge_i32_e64 s[24:25], v222, v203
	v_fmac_f32_e32 v75, 0x3f317218, v73
	v_fma_f32 v73, v76, s47, -v75
	v_add_f32_e32 v76, 1.0, v241
	v_log_f32_e32 v76, v76
	v_max_f32_e32 v242, 0, v91
	s_and_b64 s[24:25], s[78:79], s[24:25]
	v_cmp_ge_i32_e64 s[26:27], v223, v203
	v_fmac_f32_e32 v242, 0x3f317218, v76
	v_cndmask_b32_e64 v241, v73, v227, s[24:25]
	v_fma_f32 v73, v77, s47, -v242
	s_and_b64 s[26:27], s[78:79], s[26:27]
	v_cndmask_b32_e64 v243, v73, v227, s[26:27]
	v_mul_f32_e32 v73, 0x3db504f3, v78
	v_mul_f32_e64 v76, |v73|, s48
	v_exp_f32_e32 v76, v76
	v_max_f32_e32 v73, 0, v73
	v_cmp_ge_i32_e64 s[28:29], v224, v203
	s_and_b64 s[28:29], s[78:79], s[28:29]
	v_add_f32_e32 v76, 1.0, v76
	v_log_f32_e32 v76, v76
	v_cmp_ge_i32_e64 s[30:31], v225, v203
	s_and_b64 s[30:31], s[78:79], s[30:31]
	v_cmp_ge_i32_e64 s[36:37], v229, v203
	v_fmac_f32_e32 v73, 0x3f317218, v76
	v_fma_f32 v76, v78, s47, -v73
	v_cndmask_b32_e64 v244, v76, v227, s[28:29]
	v_mul_f32_e32 v76, 0x3db504f3, v79
	v_mul_f32_e64 v77, |v76|, s48
	v_exp_f32_e32 v77, v77
	v_max_f32_e32 v76, 0, v76
	s_and_b64 s[36:37], s[78:79], s[36:37]
	v_cmp_ge_i32_e64 s[38:39], v230, v203
	v_add_f32_e32 v77, 1.0, v77
	v_log_f32_e32 v77, v77
	s_and_b64 s[38:39], s[78:79], s[38:39]
	v_fmac_f32_e32 v76, 0x3f317218, v77
	v_fma_f32 v77, v79, s47, -v76
	v_cndmask_b32_e64 v245, v77, v227, s[30:31]
	v_mul_f32_e32 v77, 0x3db504f3, v80
	v_mul_f32_e64 v78, |v77|, s48
	v_exp_f32_e32 v78, v78
	v_max_f32_e32 v77, 0, v77
	v_add_f32_e32 v78, 1.0, v78
	v_log_f32_e32 v78, v78
	s_nop 0
	v_fmac_f32_e32 v77, 0x3f317218, v78
	v_fma_f32 v78, v80, s47, -v77
	v_cndmask_b32_e64 v246, v78, v227, s[36:37]
	v_mul_f32_e32 v78, 0x3db504f3, v81
	v_mul_f32_e64 v79, |v78|, s48
	v_exp_f32_e32 v79, v79
	v_max_f32_e32 v78, 0, v78
	v_add_f32_e32 v79, 1.0, v79
	v_log_f32_e32 v79, v79
	s_nop 0
	v_fmac_f32_e32 v78, 0x3f317218, v79
	v_fma_f32 v79, v81, s47, -v78
	v_cndmask_b32_e64 v247, v79, v227, s[38:39]
	v_cndmask_b32_e64 v203, -v77, 0, s[36:37]
	v_cndmask_b32_e64 v77, -v240, 0, s[20:21]
	v_cndmask_b32_e64 v240, -v72, 0, s[18:19]
	v_cndmask_b32_e64 v72, -v235, 0, s[16:17]
	v_cndmask_b32_e64 v233, -v233, 0, s[14:15]
	v_cndmask_b32_e64 v79, -v236, 0, s[12:13]
	v_cndmask_b32_e64 v91, -v76, 0, s[30:31]
	v_cndmask_b32_e64 v76, -v96, 0, s[8:9]
	v_add_f32_e32 v79, v79, v233
	v_add_f32_e32 v96, v72, v240
	v_add_f32_e32 v81, v79, v96
	v_mov_b32_e32 v72, v81
	v_mov_b32_e32 v79, v81
	v_cndmask_b32_e64 v242, -v242, 0, s[26:27]
	v_cndmask_b32_e64 v75, -v75, 0, s[24:25]
	v_cndmask_b32_e64 v249, -v74, 0, s[22:23]
	v_permlane32_swap_b32_e32 v72, v79
	v_cndmask_b32_e64 v74, -v97, 0, s[10:11]
	v_cndmask_b32_e64 v79, v72, v79, s[4:5]
	v_add_f32_e32 v72, v77, v249
	v_add_f32_e32 v97, v75, v242
	v_add_f32_e32 v72, v72, v97
	v_mov_b32_e32 v75, v72
	v_mov_b32_e32 v77, v72
	s_nop 1
	v_permlane32_swap_b32_e32 v75, v77
	v_cndmask_b32_e64 v235, v75, v77, s[4:5]
	v_cndmask_b32_e64 v248, -v78, 0, s[38:39]
	v_cndmask_b32_e64 v73, -v73, 0, s[28:29]
	v_add_f32_e32 v77, v72, v235
	v_mov_b32_e32 v72, v92
	v_cndmask_b32_e64 v78, -v95, 0, s[6:7]
	v_cndmask_b32_e64 v80, -v94, 0, vcc
	v_add_f32_e32 v95, v203, v248
	v_pk_add_f32 v[72:73], v[72:73], v[90:91]
	v_mov_b32_e32 v94, v93
	v_pk_add_f32 v[72:73], v[72:73], v[94:95]
	v_pk_add_f32 v[80:81], v[80:81], v[78:79]
	v_mov_b32_e32 v75, v73
	v_mov_b32_e32 v90, v73
	s_nop 1
	v_permlane32_swap_b32_e32 v75, v90
	v_cndmask_b32_e64 v203, v75, v90, s[4:5]
	v_pk_add_f32 v[72:73], v[202:203], v[72:73]
	s_nop 0
	v_mov_b32_e32 v75, v73
	v_pk_add_f32 v[76:77], v[76:77], v[74:75]
	s_nop 0
	v_pk_add_f32 v[80:81], v[80:81], v[76:77]
	v_add_f32_e32 v78, v78, v76
	v_mov_b32_e32 v75, v80
	v_mov_b32_e32 v90, v80
	s_nop 1
	v_permlane32_swap_b32_e32 v75, v90
	v_cndmask_b32_e64 v75, v75, v90, s[4:5]
	v_add_f32_e32 v90, v72, v81
	v_cndmask_b32_e64 v92, 0, v75, s[4:5]
	v_add_f32_e32 v90, v92, v90
	v_add_f32_e32 v68, v68, v90
	v_add_f32_e32 v67, v67, v90
	v_add_f32_e32 v66, v66, v90
	v_add_f32_e32 v69, v69, v90
	v_add_f32_e32 v68, v74, v68
	v_add_f32_e32 v67, v76, v67
	v_add_f32_e32 v66, v78, v66
	v_mul_f32_e32 v69, 0x3fb8aa3b, v69
	v_mul_f32_e32 v68, 0x3fb8aa3b, v68
	v_mul_f32_e32 v67, 0x3fb8aa3b, v67
	v_mul_f32_e32 v66, 0x3fb8aa3b, v66
	v_exp_f32_e32 v69, v69
	v_exp_f32_e32 v68, v68
	v_exp_f32_e32 v67, v67
	v_exp_f32_e32 v66, v66
	v_add_f32_e32 v74, v80, v75
	v_add_f32_e32 v75, v72, v77
	v_cndmask_b32_e64 v76, 0, v79, s[4:5]
	v_add_f32_e32 v75, v76, v75
	v_add_f32_e32 v76, v233, v96
	v_add_f32_e32 v78, v237, v75
	v_add_f32_e32 v71, v71, v75
	v_add_f32_e32 v70, v70, v75
	v_add_f32_e32 v77, v234, v75
	v_add_f32_e32 v78, v240, v78
	v_add_f32_e32 v71, v96, v71
	v_add_f32_e32 v70, v76, v70
	v_mul_f32_e32 v77, 0x3fb8aa3b, v77
	v_mul_f32_e32 v78, 0x3fb8aa3b, v78
	v_mul_f32_e32 v71, 0x3fb8aa3b, v71
	v_mul_f32_e32 v70, 0x3fb8aa3b, v70
	v_exp_f32_e32 v77, v77
	v_exp_f32_e32 v78, v78
	v_exp_f32_e32 v71, v71
	v_exp_f32_e32 v70, v70
	v_add_f32_e32 v73, v72, v73
	v_cndmask_b32_e64 v75, 0, v235, s[4:5]
	v_add_f32_e32 v73, v75, v73
	v_add_f32_e32 v75, v249, v97
	v_add_f32_e32 v76, v243, v73
	v_add_f32_e32 v79, v241, v73
	v_add_f32_e32 v80, v238, v73
	v_add_f32_e32 v73, v239, v73
	v_add_f32_e32 v79, v242, v79
	v_add_f32_e32 v80, v97, v80
	v_add_f32_e32 v73, v75, v73
	v_mul_f32_e32 v76, 0x3fb8aa3b, v76
	v_mul_f32_e32 v79, 0x3fb8aa3b, v79
	v_mul_f32_e32 v80, 0x3fb8aa3b, v80
	v_mul_f32_e32 v73, 0x3fb8aa3b, v73
	v_exp_f32_e32 v76, v76
	v_exp_f32_e32 v79, v79
	v_exp_f32_e32 v80, v80
	v_exp_f32_e32 v73, v73
	v_add_f32_e32 v75, 0, v72
	v_cndmask_b32_e64 v90, 0, v203, s[4:5]
	v_add_f32_e32 v75, v75, v90
	v_add_f32_e32 v90, v91, v95
	v_add_f32_e32 v91, v247, v75
	v_add_f32_e32 v92, v246, v75
	v_add_f32_e32 v93, v245, v75
	v_add_f32_e32 v75, v244, v75
	v_add_f32_e32 v92, v248, v92
	v_add_f32_e32 v93, v95, v93
	v_add_f32_e32 v75, v90, v75
	v_mul_f32_e32 v91, 0x3fb8aa3b, v91
	v_mul_f32_e32 v92, 0x3fb8aa3b, v92
	v_mul_f32_e32 v93, 0x3fb8aa3b, v93
	v_mul_f32_e32 v75, 0x3fb8aa3b, v75
	v_exp_f32_e32 v91, v91
	v_exp_f32_e32 v92, v92
	v_exp_f32_e32 v93, v93
	v_exp_f32_e32 v75, v75
	s_waitcnt vmcnt(15)
	ds_write_b128 v232, v[130:133]
	s_waitcnt vmcnt(14)
	ds_write_b128 v232, v[134:137] offset:2048
	s_waitcnt vmcnt(13)
	ds_write_b128 v232, v[138:141] offset:256
	s_waitcnt vmcnt(12)
	ds_write_b128 v232, v[142:145] offset:2304
	s_waitcnt vmcnt(11)
	ds_write_b128 v232, v[146:149] offset:4096
	s_waitcnt vmcnt(10)
	ds_write_b128 v232, v[150:153] offset:6144
	s_waitcnt vmcnt(9)
	ds_write_b128 v232, v[154:157] offset:4352
	s_waitcnt vmcnt(8)
	ds_write_b128 v232, v[158:161] offset:6400
	s_waitcnt vmcnt(7)
	ds_write_b128 v232, v[162:165] offset:8192
	s_waitcnt vmcnt(6)
	ds_write_b128 v232, v[166:169] offset:10240
	s_waitcnt vmcnt(5)
	ds_write_b128 v232, v[170:173] offset:8448
	s_waitcnt vmcnt(4)
	ds_write_b128 v232, v[174:177] offset:10496
	s_waitcnt vmcnt(3)
	ds_write_b128 v232, v[178:181] offset:12288
	s_waitcnt vmcnt(2)
	ds_write_b128 v232, v[182:185] offset:14336
	s_waitcnt vmcnt(1)
	ds_write_b128 v232, v[186:189] offset:12544
	s_waitcnt vmcnt(0)
	ds_write_b128 v232, v[190:193] offset:14592
	s_waitcnt lgkmcnt(0)
	v_add_f32_e32 v74, v74, v81
	v_add_f32_e32 v202, v72, v74
	v_cvt_pk_bf16_f32 v66, v66, v67
	v_cvt_pk_bf16_f32 v67, v68, v69
	v_cvt_pk_bf16_f32 v68, v70, v71
	v_cvt_pk_bf16_f32 v69, v78, v77
	v_cvt_pk_bf16_f32 v70, v73, v80
	v_cvt_pk_bf16_f32 v71, v79, v76
	v_cvt_pk_bf16_f32 v72, v75, v93
	v_cvt_pk_bf16_f32 v73, v92, v91
	v_permlane32_swap_b32_e32 v66, v68
	v_permlane32_swap_b32_e32 v70, v72
	v_permlane32_swap_b32_e32 v87, v89
	v_permlane32_swap_b32_e32 v83, v85
	v_permlane32_swap_b32_e32 v67, v69
	v_permlane32_swap_b32_e32 v71, v73
	ds_read_b64_tr_b16 v[74:75], v231 offset:0
	ds_read_b64_tr_b16 v[76:77], v231 offset:0x800
	ds_read_b64_tr_b16 v[78:79], v231 offset:0x1000
	ds_read_b64_tr_b16 v[80:81], v231 offset:0x1800
	ds_read_b64_tr_b16 v[90:91], v231 offset:0x2000
	ds_read_b64_tr_b16 v[92:93], v231 offset:0x2800
	ds_read_b64_tr_b16 v[94:95], v231 offset:0x3000
	ds_read_b64_tr_b16 v[96:97], v231 offset:0x3800
	s_waitcnt lgkmcnt(0)
	s_nop 0
	v_mfma_f32_32x32x16_bf16 v[2:17], v[66:69], v[74:77], v[2:17]
	ds_read_b64_tr_b16 v[74:75], v231 offset:0x200
	ds_read_b64_tr_b16 v[76:77], v231 offset:0xa00
	v_mfma_f32_32x32x16_bf16 v[2:17], v[70:73], v[78:81], v[2:17]
	ds_read_b64_tr_b16 v[78:79], v231 offset:0x1200
	ds_read_b64_tr_b16 v[80:81], v231 offset:0x1a00
	v_mfma_f32_32x32x16_bf16 v[2:17], v[86:89], v[90:93], v[2:17]
	ds_read_b64_tr_b16 v[90:91], v231 offset:0x2200
	ds_read_b64_tr_b16 v[92:93], v231 offset:0x2a00
	ds_read_b64_tr_b16 v[130:131], v231 offset:0x3200
	ds_read_b64_tr_b16 v[132:133], v231 offset:0x3a00
	s_waitcnt lgkmcnt(0)
	v_mfma_f32_32x32x16_bf16 v[2:17], v[82:85], v[94:97], v[2:17]
	v_mfma_f32_32x32x16_bf16 v[18:33], v[66:69], v[74:77], v[18:33]
	ds_read_b64_tr_b16 v[74:75], v231 offset:0x400
	ds_read_b64_tr_b16 v[76:77], v231 offset:0xc00
	v_mfma_f32_32x32x16_bf16 v[18:33], v[70:73], v[78:81], v[18:33]
	ds_read_b64_tr_b16 v[78:79], v231 offset:0x1400
	ds_read_b64_tr_b16 v[80:81], v231 offset:0x1c00
	v_mfma_f32_32x32x16_bf16 v[18:33], v[86:89], v[90:93], v[18:33]
	ds_read_b64_tr_b16 v[90:91], v231 offset:0x2400
	ds_read_b64_tr_b16 v[92:93], v231 offset:0x2c00
	ds_read_b64_tr_b16 v[94:95], v231 offset:0x3400
	ds_read_b64_tr_b16 v[96:97], v231 offset:0x3c00
	s_waitcnt lgkmcnt(0)
	v_mfma_f32_32x32x16_bf16 v[18:33], v[82:85], v[130:133], v[18:33]
	v_mfma_f32_32x32x16_bf16 v[34:49], v[66:69], v[74:77], v[34:49]
	ds_read_b64_tr_b16 v[74:75], v231 offset:0x600
	ds_read_b64_tr_b16 v[76:77], v231 offset:0xe00
	v_mfma_f32_32x32x16_bf16 v[34:49], v[70:73], v[78:81], v[34:49]
	ds_read_b64_tr_b16 v[78:79], v231 offset:0x1600
	ds_read_b64_tr_b16 v[80:81], v231 offset:0x1e00
	v_mfma_f32_32x32x16_bf16 v[34:49], v[86:89], v[90:93], v[34:49]
	ds_read_b64_tr_b16 v[90:91], v231 offset:0x2600
	ds_read_b64_tr_b16 v[92:93], v231 offset:0x2e00
	ds_read_b64_tr_b16 v[130:131], v231 offset:0x3600
	ds_read_b64_tr_b16 v[132:133], v231 offset:0x3e00
	s_waitcnt lgkmcnt(0)
	v_mfma_f32_32x32x16_bf16 v[34:49], v[82:85], v[94:97], v[34:49]
	v_mfma_f32_32x32x16_bf16 v[50:65], v[66:69], v[74:77], v[50:65]
	v_cmp_gt_f32_e32 vcc, s49, v202
	s_cmp_lg_u64 vcc, exec
	s_cselect_b64 s[6:7], -1, 0
	s_cmp_lg_u32 s80, s81
	s_cselect_b64 s[8:9], -1, 0
	s_and_b64 s[6:7], s[8:9], s[6:7]
	v_add_u32_e32 v214, 64, v214
	v_mfma_f32_32x32x16_bf16 v[50:65], v[70:73], v[78:81], v[50:65]
	s_add_i32 s81, s81, 1
	s_sub_i32 s54, s54, 64
	s_and_b64 vcc, exec, s[6:7]
	v_mfma_f32_32x32x16_bf16 v[50:65], v[86:89], v[90:93], v[50:65]
	v_mfma_f32_32x32x16_bf16 v[50:65], v[82:85], v[130:133], v[50:65]
	s_cbranch_vccnz .LBB0_381
	v_lshlrev_b32_e32 v69, 2, v205
	s_waitcnt lgkmcnt(0)
	global_load_dword v68, v69, s[56:57]
	global_load_dword v67, v69, s[56:57] offset:128
	global_load_dword v66, v69, s[56:57] offset:256
	v_and_b32_e32 v70, 64, v228
	global_load_dword v69, v69, s[56:57] offset:384
	v_xor_b32_e32 v75, 1, v228
	v_add_u32_e32 v83, 64, v70
	v_lshlrev_b32_e32 v71, 10, v206
	v_lshlrev_b32_e32 v72, 1, v205
	v_mul_f32_e32 v73, v18, v18
	v_mul_f32_e32 v74, v50, v50
	v_cmp_lt_i32_e32 vcc, v75, v83
	v_add3_u32 v70, s42, v71, v72
	v_fmac_f32_e32 v73, v2, v2
	v_fmac_f32_e32 v74, v34, v34
	v_cndmask_b32_e32 v72, v228, v75, vcc
	v_add_f32_e32 v71, v73, v74
	v_lshlrev_b32_e32 v75, 2, v72
	ds_bpermute_b32 v72, v75, v71
	v_xor_b32_e32 v76, 2, v228
	v_cmp_lt_i32_e32 vcc, v76, v83
	v_mul_f32_e32 v80, v19, v19
	v_mul_f32_e32 v81, v51, v51
	v_cndmask_b32_e32 v73, v228, v76, vcc
	v_fmac_f32_e32 v80, v3, v3
	v_fmac_f32_e32 v81, v35, v35
	v_lshlrev_b32_e32 v74, 2, v73
	s_waitcnt lgkmcnt(0)
	v_add_f32_e32 v71, v71, v72
	v_add_f32_e32 v76, v80, v81
	ds_bpermute_b32 v72, v74, v71
	ds_bpermute_b32 v80, v75, v76
	v_xor_b32_e32 v77, 4, v228
	v_cmp_lt_i32_e32 vcc, v77, v83
	v_xor_b32_e32 v78, 8, v228
	s_waitcnt lgkmcnt(1)
	v_add_f32_e32 v71, v71, v72
	v_cndmask_b32_e32 v73, v228, v77, vcc
	v_lshlrev_b32_e32 v73, 2, v73
	s_waitcnt lgkmcnt(0)
	v_add_f32_e32 v76, v76, v80
	ds_bpermute_b32 v80, v73, v71
	v_cmp_lt_i32_e32 vcc, v78, v83
	v_xor_b32_e32 v79, 16, v228
	ds_bpermute_b32 v77, v74, v76
	v_cndmask_b32_e32 v72, v228, v78, vcc
	v_lshlrev_b32_e32 v72, 2, v72
	s_waitcnt lgkmcnt(1)
	v_add_f32_e32 v78, v71, v80
	ds_bpermute_b32 v80, v72, v78
	v_cmp_lt_i32_e32 vcc, v79, v83
	s_waitcnt lgkmcnt(1)
	v_add_f32_e32 v76, v76, v77
	ds_bpermute_b32 v77, v73, v76
	v_cndmask_b32_e32 v71, v228, v79, vcc
	v_lshlrev_b32_e32 v71, 2, v71
	s_waitcnt lgkmcnt(1)
	v_add_f32_e32 v78, v78, v80
	ds_bpermute_b32 v79, v71, v78
	v_mul_f32_e32 v82, v20, v20
	v_fmac_f32_e32 v82, v4, v4
	s_waitcnt lgkmcnt(1)
	v_add_f32_e32 v76, v76, v77
	ds_bpermute_b32 v77, v72, v76
	s_waitcnt lgkmcnt(1)
	v_add_f32_e32 v78, v78, v79
	v_fmamk_f32 v78, v78, 0x3c000000, v226
	v_rsq_f32_e32 v78, v78
	s_lshl_b32 s4, s65, 18
	s_waitcnt lgkmcnt(0)
	v_add_f32_e32 v76, v76, v77
	ds_bpermute_b32 v77, v71, v76
	v_mul_f32_e32 v2, v2, v78
	v_mul_f32_e32 v18, v18, v78
	v_mul_f32_e32 v34, v34, v78
	v_mul_f32_e32 v50, v50, v78
	s_waitcnt lgkmcnt(0)
	v_add_f32_e32 v76, v76, v77
	v_fmamk_f32 v76, v76, 0x3c000000, v226
	v_rsq_f32_e32 v76, v76
	v_readlane_b32 s5, v255, 15
	s_add_u32 s4, s5, s4
	v_readlane_b32 s5, v255, 16
	v_mul_f32_e32 v3, v3, v76
	s_addc_u32 s5, s5, 0
	s_lshl_b32 s6, s51, 1
	s_add_u32 s4, s4, s6
	s_addc_u32 s5, s5, 0
	v_lshlrev_b32_e32 v214, 1, v195
	v_cmp_gt_i32_e32 vcc, 32, v194
	s_waitcnt vmcnt(3)
	v_mul_f32_e32 v2, v68, v2
	s_waitcnt vmcnt(2)
	v_mul_f32_e32 v18, v67, v18
	s_waitcnt vmcnt(1)
	v_mul_f32_e32 v34, v66, v34
	v_cvt_pk_bf16_f32 v2, v2, s0
	v_cvt_pk_bf16_f32 v18, v18, s0
	v_cvt_pk_bf16_f32 v34, v34, s0
	ds_write_b16 v70, v2
	ds_write_b16 v70, v18 offset:64
	ds_write_b16 v70, v34 offset:128
	v_mul_f32_e32 v2, v52, v52
	v_fmac_f32_e32 v2, v36, v36
	v_add_f32_e32 v2, v82, v2
	ds_bpermute_b32 v18, v75, v2
	s_waitcnt vmcnt(0)
	v_mul_f32_e32 v34, v69, v50
	v_mul_f32_e32 v3, v68, v3
	v_cvt_pk_bf16_f32 v34, v34, s0
	v_cvt_pk_bf16_f32 v3, v3, s0
	s_waitcnt lgkmcnt(0)
	v_add_f32_e32 v2, v2, v18
	ds_bpermute_b32 v18, v74, v2
	ds_write_b16 v70, v34 offset:192
	ds_write_b16 v70, v3 offset:256
	v_mul_f32_e32 v3, v19, v76
	v_mul_f32_e32 v19, v21, v21
	s_waitcnt lgkmcnt(2)
	v_add_f32_e32 v2, v2, v18
	ds_bpermute_b32 v18, v73, v2
	v_mul_f32_e32 v34, v53, v53
	v_fmac_f32_e32 v19, v5, v5
	v_fmac_f32_e32 v34, v37, v37
	v_add_f32_e32 v19, v19, v34
	s_waitcnt lgkmcnt(0)
	v_add_f32_e32 v2, v2, v18
	ds_bpermute_b32 v18, v72, v2
	ds_bpermute_b32 v34, v75, v19
	v_mul_f32_e32 v3, v67, v3
	v_cvt_pk_bf16_f32 v3, v3, s0
	ds_write_b16 v70, v3 offset:320
	s_waitcnt lgkmcnt(2)
	v_add_f32_e32 v2, v2, v18
	ds_bpermute_b32 v18, v71, v2
	v_mul_f32_e32 v3, v35, v76
	v_mul_f32_e32 v3, v66, v3
	v_cvt_pk_bf16_f32 v3, v3, s0
	ds_write_b16 v70, v3 offset:384
	s_waitcnt lgkmcnt(1)
	v_add_f32_e32 v2, v2, v18
	v_add_f32_e32 v18, v19, v34
	v_fmamk_f32 v2, v2, 0x3c000000, v226
	ds_bpermute_b32 v19, v74, v18
	v_rsq_f32_e32 v2, v2
	v_mul_f32_e32 v3, v51, v76
	v_mul_f32_e32 v3, v69, v3
	v_cvt_pk_bf16_f32 v3, v3, s0
	ds_write_b16 v70, v3 offset:448
	v_mul_f32_e32 v3, v4, v2
	s_waitcnt lgkmcnt(1)
	v_add_f32_e32 v4, v18, v19
	ds_bpermute_b32 v18, v73, v4
	v_mul_f32_e32 v3, v68, v3
	v_cvt_pk_bf16_f32 v3, v3, s0
	ds_write_b16 v70, v3 offset:512
	v_mul_f32_e32 v3, v20, v2
	s_waitcnt lgkmcnt(1)
	v_add_f32_e32 v4, v4, v18
	ds_bpermute_b32 v18, v72, v4
	v_mul_f32_e32 v3, v67, v3
	v_cvt_pk_bf16_f32 v3, v3, s0
	ds_write_b16 v70, v3 offset:576
	v_mul_f32_e32 v3, v36, v2
	s_waitcnt lgkmcnt(1)
	v_add_f32_e32 v4, v4, v18
	ds_bpermute_b32 v18, v71, v4
	v_mul_f32_e32 v3, v66, v3
	v_cvt_pk_bf16_f32 v3, v3, s0
	ds_write_b16 v70, v3 offset:640
	v_mul_f32_e32 v2, v52, v2
	s_waitcnt lgkmcnt(1)
	v_add_f32_e32 v3, v4, v18
	v_mul_f32_e32 v4, v22, v22
	v_mul_f32_e32 v18, v54, v54
	v_fmac_f32_e32 v4, v6, v6
	v_fmac_f32_e32 v18, v38, v38
	v_add_f32_e32 v4, v4, v18
	ds_bpermute_b32 v18, v75, v4
	v_fmamk_f32 v3, v3, 0x3c000000, v226
	v_rsq_f32_e32 v3, v3
	v_mul_f32_e32 v2, v69, v2
	v_cvt_pk_bf16_f32 v2, v2, s0
	s_waitcnt lgkmcnt(0)
	v_add_f32_e32 v4, v4, v18
	ds_write_b16 v70, v2 offset:704
	v_mul_f32_e32 v2, v5, v3
	ds_bpermute_b32 v5, v74, v4
	v_mul_f32_e32 v2, v68, v2
	v_cvt_pk_bf16_f32 v2, v2, s0
	ds_write_b16 v70, v2 offset:768
	v_mul_f32_e32 v2, v21, v3
	s_waitcnt lgkmcnt(1)
	v_add_f32_e32 v4, v4, v5
	ds_bpermute_b32 v5, v73, v4
	v_mul_f32_e32 v2, v67, v2
	v_cvt_pk_bf16_f32 v2, v2, s0
	ds_write_b16 v70, v2 offset:832
	v_mul_f32_e32 v2, v37, v3
	s_waitcnt lgkmcnt(1)
	v_add_f32_e32 v4, v4, v5
	ds_bpermute_b32 v5, v72, v4
	v_mul_f32_e32 v2, v66, v2
	v_cvt_pk_bf16_f32 v2, v2, s0
	ds_write_b16 v70, v2 offset:896
	v_mul_f32_e32 v2, v53, v3
	s_waitcnt lgkmcnt(1)
	v_add_f32_e32 v3, v4, v5
	v_mul_f32_e32 v5, v23, v23
	v_mul_f32_e32 v18, v55, v55
	v_fmac_f32_e32 v5, v7, v7
	v_fmac_f32_e32 v18, v39, v39
	v_add_f32_e32 v5, v5, v18
	ds_bpermute_b32 v4, v71, v3
	ds_bpermute_b32 v18, v75, v5
	v_mul_f32_e32 v2, v69, v2
	v_cvt_pk_bf16_f32 v2, v2, s0
	ds_write_b16 v70, v2 offset:960
	s_waitcnt lgkmcnt(2)
	v_add_f32_e32 v3, v3, v4
	s_waitcnt lgkmcnt(1)
	v_add_f32_e32 v4, v5, v18
	ds_bpermute_b32 v5, v74, v4
	v_fmamk_f32 v3, v3, 0x3c000000, v226
	v_rsq_f32_e32 v3, v3
	s_waitcnt lgkmcnt(0)
	v_add_f32_e32 v4, v4, v5
	ds_bpermute_b32 v5, v73, v4
	v_mul_f32_e32 v2, v6, v3
	v_mul_f32_e32 v2, v68, v2
	v_cvt_pk_bf16_f32 v2, v2, s0
	ds_write_b16 v70, v2 offset:2048
	s_waitcnt lgkmcnt(1)
	v_add_f32_e32 v4, v4, v5
	ds_bpermute_b32 v5, v72, v4
	v_mul_f32_e32 v2, v22, v3
	v_mul_f32_e32 v2, v67, v2
	v_cvt_pk_bf16_f32 v2, v2, s0
	ds_write_b16 v70, v2 offset:2112
	s_waitcnt lgkmcnt(1)
	v_add_f32_e32 v4, v4, v5
	ds_bpermute_b32 v5, v71, v4
	v_mul_f32_e32 v2, v38, v3
	v_mul_f32_e32 v2, v66, v2
	v_cvt_pk_bf16_f32 v2, v2, s0
	ds_write_b16 v70, v2 offset:2176
	v_mul_f32_e32 v2, v54, v3
	s_waitcnt lgkmcnt(1)
	v_add_f32_e32 v3, v4, v5
	v_mul_f32_e32 v4, v24, v24
	v_mul_f32_e32 v5, v56, v56
	v_fmac_f32_e32 v4, v8, v8
	v_fmac_f32_e32 v5, v40, v40
	v_add_f32_e32 v4, v4, v5
	ds_bpermute_b32 v5, v75, v4
	v_fmamk_f32 v3, v3, 0x3c000000, v226
	v_rsq_f32_e32 v3, v3
	v_mul_f32_e32 v2, v69, v2
	v_cvt_pk_bf16_f32 v2, v2, s0
	s_waitcnt lgkmcnt(0)
	v_add_f32_e32 v4, v4, v5
	ds_bpermute_b32 v5, v74, v4
	ds_write_b16 v70, v2 offset:2240
	v_mul_f32_e32 v2, v7, v3
	v_mul_f32_e32 v2, v68, v2
	v_cvt_pk_bf16_f32 v2, v2, s0
	s_waitcnt lgkmcnt(1)
	v_add_f32_e32 v4, v4, v5
	ds_bpermute_b32 v5, v73, v4
	ds_write_b16 v70, v2 offset:2304
	v_mul_f32_e32 v2, v23, v3
	v_mul_f32_e32 v2, v67, v2
	v_cvt_pk_bf16_f32 v2, v2, s0
	s_waitcnt lgkmcnt(1)
	v_add_f32_e32 v4, v4, v5
	ds_bpermute_b32 v5, v72, v4
	ds_write_b16 v70, v2 offset:2368
	v_mul_f32_e32 v2, v39, v3
	v_mul_f32_e32 v2, v66, v2
	v_cvt_pk_bf16_f32 v2, v2, s0
	ds_write_b16 v70, v2 offset:2432
	v_mul_f32_e32 v2, v55, v3
	s_waitcnt lgkmcnt(2)
	v_add_f32_e32 v3, v4, v5
	v_mul_f32_e32 v5, v25, v25
	v_mul_f32_e32 v6, v57, v57
	v_fmac_f32_e32 v5, v9, v9
	v_fmac_f32_e32 v6, v41, v41
	v_add_f32_e32 v5, v5, v6
	ds_bpermute_b32 v6, v75, v5
	ds_bpermute_b32 v4, v71, v3
	v_mul_f32_e32 v2, v69, v2
	v_cvt_pk_bf16_f32 v2, v2, s0
	ds_write_b16 v70, v2 offset:2496
	s_waitcnt lgkmcnt(2)
	v_add_f32_e32 v2, v5, v6
	s_waitcnt lgkmcnt(1)
	v_add_f32_e32 v3, v3, v4
	ds_bpermute_b32 v4, v74, v2
	v_fmamk_f32 v3, v3, 0x3c000000, v226
	v_rsq_f32_e32 v3, v3
	v_mul_f32_e32 v6, v58, v58
	v_fmac_f32_e32 v6, v42, v42
	s_waitcnt lgkmcnt(0)
	v_add_f32_e32 v2, v2, v4
	v_mul_f32_e32 v5, v8, v3
	ds_bpermute_b32 v4, v73, v2
	v_mul_f32_e32 v5, v68, v5
	v_cvt_pk_bf16_f32 v5, v5, s0
	ds_write_b16 v70, v5 offset:2560
	v_mul_f32_e32 v5, v24, v3
	v_mul_f32_e32 v5, v67, v5
	v_cvt_pk_bf16_f32 v5, v5, s0
	s_waitcnt lgkmcnt(1)
	v_add_f32_e32 v2, v2, v4
	ds_write_b16 v70, v5 offset:2624
	ds_bpermute_b32 v4, v72, v2
	v_mul_f32_e32 v5, v40, v3
	v_mul_f32_e32 v5, v66, v5
	v_cvt_pk_bf16_f32 v5, v5, s0
	ds_write_b16 v70, v5 offset:2688
	v_mul_f32_e32 v5, v26, v26
	v_fmac_f32_e32 v5, v10, v10
	s_waitcnt lgkmcnt(1)
	v_add_f32_e32 v2, v2, v4
	v_add_f32_e32 v5, v5, v6
	ds_bpermute_b32 v4, v71, v2
	ds_bpermute_b32 v6, v75, v5
	v_mul_f32_e32 v3, v56, v3
	v_mul_f32_e32 v3, v69, v3
	v_cvt_pk_bf16_f32 v3, v3, s0
	s_waitcnt lgkmcnt(1)
	v_add_f32_e32 v2, v2, v4
	s_waitcnt lgkmcnt(0)
	v_add_f32_e32 v4, v5, v6
	ds_bpermute_b32 v5, v74, v4
	v_fmamk_f32 v2, v2, 0x3c000000, v226
	v_rsq_f32_e32 v2, v2
	ds_write_b16 v70, v3 offset:2752
	v_mul_f32_e32 v6, v60, v60
	s_waitcnt lgkmcnt(1)
	v_add_f32_e32 v4, v4, v5
	ds_bpermute_b32 v5, v73, v4
	v_mul_f32_e32 v3, v9, v2
	v_mul_f32_e32 v3, v68, v3
	v_cvt_pk_bf16_f32 v3, v3, s0
	ds_write_b16 v70, v3 offset:2816
	s_waitcnt lgkmcnt(1)
	v_add_f32_e32 v4, v4, v5
	ds_bpermute_b32 v5, v72, v4
	v_mul_f32_e32 v3, v25, v2
	v_mul_f32_e32 v3, v67, v3
	v_cvt_pk_bf16_f32 v3, v3, s0
	ds_write_b16 v70, v3 offset:2880
	s_waitcnt lgkmcnt(1)
	v_add_f32_e32 v4, v4, v5
	ds_bpermute_b32 v5, v71, v4
	v_mul_f32_e32 v3, v41, v2
	v_mul_f32_e32 v3, v66, v3
	v_cvt_pk_bf16_f32 v3, v3, s0
	ds_write_b16 v70, v3 offset:2944
	s_waitcnt lgkmcnt(1)
	v_add_f32_e32 v3, v4, v5
	v_mul_f32_e32 v4, v27, v27
	v_mul_f32_e32 v5, v59, v59
	v_fmac_f32_e32 v4, v11, v11
	v_fmac_f32_e32 v5, v43, v43
	v_add_f32_e32 v4, v4, v5
	ds_bpermute_b32 v5, v75, v4
	v_fmamk_f32 v3, v3, 0x3c000000, v226
	v_rsq_f32_e32 v3, v3
	v_mul_f32_e32 v2, v57, v2
	v_mul_f32_e32 v2, v69, v2
	s_waitcnt lgkmcnt(0)
	v_add_f32_e32 v4, v4, v5
	ds_bpermute_b32 v5, v74, v4
	v_cvt_pk_bf16_f32 v2, v2, s0
	ds_write_b16 v70, v2 offset:3008
	v_mul_f32_e32 v2, v10, v3
	v_mul_f32_e32 v2, v68, v2
	s_waitcnt lgkmcnt(1)
	v_add_f32_e32 v4, v4, v5
	ds_bpermute_b32 v5, v73, v4
	v_cvt_pk_bf16_f32 v2, v2, s0
	ds_write_b16 v70, v2 offset:4096
	v_mul_f32_e32 v2, v26, v3
	v_mul_f32_e32 v2, v67, v2
	s_waitcnt lgkmcnt(1)
	v_add_f32_e32 v4, v4, v5
	ds_bpermute_b32 v5, v72, v4
	v_cvt_pk_bf16_f32 v2, v2, s0
	ds_write_b16 v70, v2 offset:4160
	v_mul_f32_e32 v2, v42, v3
	v_mul_f32_e32 v2, v66, v2
	v_cvt_pk_bf16_f32 v2, v2, s0
	ds_write_b16 v70, v2 offset:4224
	v_mul_f32_e32 v2, v58, v3
	s_waitcnt lgkmcnt(2)
	v_add_f32_e32 v3, v4, v5
	v_mul_f32_e32 v5, v28, v28
	v_fmac_f32_e32 v5, v12, v12
	v_fmac_f32_e32 v6, v44, v44
	v_add_f32_e32 v5, v5, v6
	ds_bpermute_b32 v4, v71, v3
	ds_bpermute_b32 v6, v75, v5
	v_mul_f32_e32 v2, v69, v2
	v_cvt_pk_bf16_f32 v2, v2, s0
	ds_write_b16 v70, v2 offset:4288
	s_waitcnt lgkmcnt(2)
	v_add_f32_e32 v3, v3, v4
	s_waitcnt lgkmcnt(1)
	v_add_f32_e32 v4, v5, v6
	ds_bpermute_b32 v5, v74, v4
	v_fmamk_f32 v3, v3, 0x3c000000, v226
	v_rsq_f32_e32 v3, v3
	v_mul_f32_e32 v6, v62, v62
	v_fmac_f32_e32 v6, v46, v46
	s_waitcnt lgkmcnt(0)
	v_add_f32_e32 v4, v4, v5
	ds_bpermute_b32 v5, v73, v4
	v_mul_f32_e32 v2, v11, v3
	v_mul_f32_e32 v2, v68, v2
	v_cvt_pk_bf16_f32 v2, v2, s0
	ds_write_b16 v70, v2 offset:4352
	s_waitcnt lgkmcnt(1)
	v_add_f32_e32 v4, v4, v5
	ds_bpermute_b32 v5, v72, v4
	v_mul_f32_e32 v2, v27, v3
	v_mul_f32_e32 v2, v67, v2
	v_cvt_pk_bf16_f32 v2, v2, s0
	ds_write_b16 v70, v2 offset:4416
	s_waitcnt lgkmcnt(1)
	v_add_f32_e32 v4, v4, v5
	ds_bpermute_b32 v5, v71, v4
	v_mul_f32_e32 v2, v43, v3
	v_mul_f32_e32 v2, v66, v2
	v_cvt_pk_bf16_f32 v2, v2, s0
	ds_write_b16 v70, v2 offset:4480
	v_mul_f32_e32 v2, v59, v3
	s_waitcnt lgkmcnt(1)
	v_add_f32_e32 v3, v4, v5
	v_mul_f32_e32 v4, v29, v29
	v_mul_f32_e32 v5, v61, v61
	v_fmac_f32_e32 v4, v13, v13
	v_fmac_f32_e32 v5, v45, v45
	v_add_f32_e32 v4, v4, v5
	ds_bpermute_b32 v5, v75, v4
	v_fmamk_f32 v3, v3, 0x3c000000, v226
	v_rsq_f32_e32 v3, v3
	v_mul_f32_e32 v2, v69, v2
	v_cvt_pk_bf16_f32 v2, v2, s0
	s_waitcnt lgkmcnt(0)
	v_add_f32_e32 v4, v4, v5
	ds_bpermute_b32 v5, v74, v4
	ds_write_b16 v70, v2 offset:4544
	v_mul_f32_e32 v2, v12, v3
	v_mul_f32_e32 v2, v68, v2
	v_cvt_pk_bf16_f32 v2, v2, s0
	s_waitcnt lgkmcnt(1)
	v_add_f32_e32 v4, v4, v5
	ds_bpermute_b32 v5, v73, v4
	ds_write_b16 v70, v2 offset:4608
	v_mul_f32_e32 v2, v28, v3
	v_mul_f32_e32 v2, v67, v2
	v_cvt_pk_bf16_f32 v2, v2, s0
	s_waitcnt lgkmcnt(1)
	v_add_f32_e32 v4, v4, v5
	ds_bpermute_b32 v5, v72, v4
	ds_write_b16 v70, v2 offset:4672
	v_mul_f32_e32 v2, v44, v3
	v_mul_f32_e32 v2, v66, v2
	v_cvt_pk_bf16_f32 v2, v2, s0
	ds_write_b16 v70, v2 offset:4736
	v_mul_f32_e32 v2, v60, v3
	s_waitcnt lgkmcnt(2)
	v_add_f32_e32 v3, v4, v5
	v_mul_f32_e32 v5, v30, v30
	v_fmac_f32_e32 v5, v14, v14
	v_add_f32_e32 v5, v5, v6
	ds_bpermute_b32 v4, v71, v3
	ds_bpermute_b32 v6, v75, v5
	v_mul_f32_e32 v2, v69, v2
	v_cvt_pk_bf16_f32 v2, v2, s0
	ds_write_b16 v70, v2 offset:4800
	s_waitcnt lgkmcnt(2)
	v_add_f32_e32 v3, v3, v4
	s_waitcnt lgkmcnt(1)
	v_add_f32_e32 v4, v5, v6
	ds_bpermute_b32 v5, v74, v4
	v_fmamk_f32 v3, v3, 0x3c000000, v226
	v_rsq_f32_e32 v3, v3
	v_mul_f32_e32 v6, v64, v64
	v_fmac_f32_e32 v6, v48, v48
	s_waitcnt lgkmcnt(0)
	v_add_f32_e32 v4, v4, v5
	ds_bpermute_b32 v5, v73, v4
	v_mul_f32_e32 v2, v13, v3
	v_mul_f32_e32 v2, v68, v2
	v_cvt_pk_bf16_f32 v2, v2, s0
	ds_write_b16 v70, v2 offset:4864
	s_waitcnt lgkmcnt(1)
	v_add_f32_e32 v4, v4, v5
	ds_bpermute_b32 v5, v72, v4
	v_mul_f32_e32 v2, v29, v3
	v_mul_f32_e32 v2, v67, v2
	v_cvt_pk_bf16_f32 v2, v2, s0
	ds_write_b16 v70, v2 offset:4928
	s_waitcnt lgkmcnt(1)
	v_add_f32_e32 v4, v4, v5
	ds_bpermute_b32 v5, v71, v4
	v_mul_f32_e32 v2, v45, v3
	v_mul_f32_e32 v2, v66, v2
	v_cvt_pk_bf16_f32 v2, v2, s0
	ds_write_b16 v70, v2 offset:4992
	v_mul_f32_e32 v2, v61, v3
	s_waitcnt lgkmcnt(1)
	v_add_f32_e32 v3, v4, v5
	v_mul_f32_e32 v4, v31, v31
	v_mul_f32_e32 v5, v63, v63
	v_fmac_f32_e32 v4, v15, v15
	v_fmac_f32_e32 v5, v47, v47
	v_add_f32_e32 v4, v4, v5
	ds_bpermute_b32 v5, v75, v4
	v_fmamk_f32 v3, v3, 0x3c000000, v226
	v_rsq_f32_e32 v3, v3
	v_mul_f32_e32 v2, v69, v2
	v_cvt_pk_bf16_f32 v2, v2, s0
	s_waitcnt lgkmcnt(0)
	v_add_f32_e32 v4, v4, v5
	ds_bpermute_b32 v5, v74, v4
	ds_write_b16 v70, v2 offset:5056
	v_mul_f32_e32 v2, v14, v3
	v_mul_f32_e32 v2, v68, v2
	v_cvt_pk_bf16_f32 v2, v2, s0
	s_waitcnt lgkmcnt(1)
	v_add_f32_e32 v4, v4, v5
	ds_bpermute_b32 v5, v73, v4
	ds_write_b16 v70, v2 offset:6144
	v_mul_f32_e32 v2, v30, v3
	v_mul_f32_e32 v2, v67, v2
	v_cvt_pk_bf16_f32 v2, v2, s0
	s_waitcnt lgkmcnt(1)
	v_add_f32_e32 v4, v4, v5
	ds_bpermute_b32 v5, v72, v4
	ds_write_b16 v70, v2 offset:6208
	v_mul_f32_e32 v2, v46, v3
	v_mul_f32_e32 v2, v66, v2
	v_cvt_pk_bf16_f32 v2, v2, s0
	ds_write_b16 v70, v2 offset:6272
	v_mul_f32_e32 v2, v62, v3
	s_waitcnt lgkmcnt(2)
	v_add_f32_e32 v3, v4, v5
	v_mul_f32_e32 v5, v32, v32
	v_fmac_f32_e32 v5, v16, v16
	v_add_f32_e32 v5, v5, v6
	ds_bpermute_b32 v6, v75, v5
	ds_bpermute_b32 v4, v71, v3
	v_mul_f32_e32 v2, v69, v2
	v_cvt_pk_bf16_f32 v2, v2, s0
	ds_write_b16 v70, v2 offset:6336
	s_waitcnt lgkmcnt(2)
	v_add_f32_e32 v2, v5, v6
	s_waitcnt lgkmcnt(1)
	v_add_f32_e32 v3, v3, v4
	ds_bpermute_b32 v4, v74, v2
	v_fmamk_f32 v3, v3, 0x3c000000, v226
	v_rsq_f32_e32 v3, v3
	v_mul_f32_e32 v6, v65, v65
	v_fmac_f32_e32 v6, v49, v49
	s_waitcnt lgkmcnt(0)
	v_add_f32_e32 v2, v2, v4
	v_mul_f32_e32 v5, v15, v3
	ds_bpermute_b32 v4, v73, v2
	v_mul_f32_e32 v5, v68, v5
	v_cvt_pk_bf16_f32 v5, v5, s0
	ds_write_b16 v70, v5 offset:6400
	v_mul_f32_e32 v5, v31, v3
	v_mul_f32_e32 v5, v67, v5
	v_cvt_pk_bf16_f32 v5, v5, s0
	s_waitcnt lgkmcnt(1)
	v_add_f32_e32 v2, v2, v4
	ds_write_b16 v70, v5 offset:6464
	ds_bpermute_b32 v4, v72, v2
	v_mul_f32_e32 v5, v47, v3
	v_mul_f32_e32 v5, v66, v5
	v_cvt_pk_bf16_f32 v5, v5, s0
	ds_write_b16 v70, v5 offset:6528
	v_mul_f32_e32 v5, v33, v33
	v_fmac_f32_e32 v5, v17, v17
	s_waitcnt lgkmcnt(1)
	v_add_f32_e32 v2, v2, v4
	v_add_f32_e32 v5, v5, v6
	ds_bpermute_b32 v4, v71, v2
	ds_bpermute_b32 v6, v75, v5
	v_mul_f32_e32 v3, v63, v3
	v_mul_f32_e32 v3, v69, v3
	v_cvt_pk_bf16_f32 v3, v3, s0
	s_waitcnt lgkmcnt(1)
	v_add_f32_e32 v2, v2, v4
	s_waitcnt lgkmcnt(0)
	v_add_f32_e32 v4, v5, v6
	ds_bpermute_b32 v5, v74, v4
	v_fmamk_f32 v2, v2, 0x3c000000, v226
	v_rsq_f32_e32 v2, v2
	ds_write_b16 v70, v3 offset:6592
	v_add_u32_e32 v6, s42, v214
	s_waitcnt lgkmcnt(1)
	v_add_f32_e32 v4, v4, v5
	ds_bpermute_b32 v5, v73, v4
	v_mul_f32_e32 v3, v16, v2
	v_mul_f32_e32 v3, v68, v3
	v_cvt_pk_bf16_f32 v3, v3, s0
	ds_write_b16 v70, v3 offset:6656
	s_waitcnt lgkmcnt(1)
	v_add_f32_e32 v4, v4, v5
	ds_bpermute_b32 v5, v72, v4
	v_mul_f32_e32 v3, v32, v2
	v_mul_f32_e32 v3, v67, v3
	v_cvt_pk_bf16_f32 v3, v3, s0
	ds_write_b16 v70, v3 offset:6720
	s_waitcnt lgkmcnt(1)
	v_add_f32_e32 v4, v4, v5
	ds_bpermute_b32 v5, v71, v4
	v_mul_f32_e32 v3, v48, v2
	v_mul_f32_e32 v3, v66, v3
	v_cvt_pk_bf16_f32 v3, v3, s0
	ds_write_b16 v70, v3 offset:6784
	s_waitcnt lgkmcnt(1)
	v_add_f32_e32 v3, v4, v5
	v_fmamk_f32 v3, v3, 0x3c000000, v226
	v_rsq_f32_e32 v3, v3
	v_mul_f32_e32 v2, v64, v2
	v_mul_f32_e32 v2, v69, v2
	v_cvt_pk_bf16_f32 v2, v2, s0
	ds_write_b16 v70, v2 offset:6848
	v_mul_f32_e32 v2, v17, v3
	v_mul_f32_e32 v2, v68, v2
	v_cvt_pk_bf16_f32 v2, v2, s0
	ds_write_b16 v70, v2 offset:6912
	v_mul_f32_e32 v2, v33, v3
	v_mul_f32_e32 v2, v67, v2
	v_cvt_pk_bf16_f32 v2, v2, s0
	ds_write_b16 v70, v2 offset:6976
	v_mul_f32_e32 v2, v49, v3
	v_mul_f32_e32 v2, v66, v2
	v_cvt_pk_bf16_f32 v2, v2, s0
	ds_write_b16 v70, v2 offset:7040
	v_mul_f32_e32 v2, v65, v3
	v_mul_f32_e32 v2, v69, v2
	v_cvt_pk_bf16_f32 v2, v2, s0
	ds_write_b16 v70, v2 offset:7104
	s_waitcnt lgkmcnt(0)
	v_lshl_add_u64 v[2:3], s[4:5], 0, v[214:215]
	v_lshl_add_u64 v[2:3], v[2:3], 0, s[66:67]
	s_and_saveexec_b64 s[4:5], vcc
	s_cbranch_execz .LBB0_384
	v_lshl_add_u32 v4, v194, 8, v6
	ds_read_b128 v[8:11], v4
	v_ashrrev_i32_e32 v195, 31, v194
	v_lshlrev_b64 v[4:5], 13, v[194:195]
	v_lshl_add_u64 v[4:5], v[2:3], 0, v[4:5]
	s_waitcnt lgkmcnt(0)
	global_store_dwordx4 v[4:5], v[8:11], off
